# DeltaNet prep: next-unit conv-row prefetch (22 loads per thread) issued at the end of segment 2 instead of the start of the forward-substitution segment (longer lead, burst lands where most waves idle
# baseline (speedup 1.0000x reference)
.LBB0_535:
	s_or_b64 exec, exec, s[10:11]
	s_add_i32 s8, s36, s50
	s_cmpk_gt_u32 s8, 0xfff
	s_cbranch_scc1 .Lpf2_done
	s_bfe_u32 s9, s8, 0x30006
	s_lshl_b32 s9, s9, 7
	s_and_b32 s10, s8, 63
	s_lshl_b32 s10, s10, 6
	s_lshr_b32 s11, s8, 9
	s_lshl_b32 s11, s11, 12
	s_or_b32 s11, s11, s10
	v_add3_u32 v0, v42, v13, s9
	v_readfirstlane_b32 s13, v10
	v_add_u32_e32 v2, 0x400, v0
	v_lshrrev_b32_e32 v3, 5, v81
	v_mul_u32_u24_e32 v3, 0x11000, v3
	v_lshl_add_u32 v2, v2, 1, v3
	v_or_b32_e32 v4, s9, v11
	v_lshlrev_b32_e32 v4, 1, v4
	s_and_b32 s45, s13, 24
	s_lshl_b32 s46, s45, 1
	s_add_i32 s46, s46, s11
	s_add_i32 s46, s46, -3
	s_mul_i32 s46, s46, 0x2200
	s_ashr_i32 s47, s46, 31
	s_add_u32 s46, s24, s46
	s_addc_u32 s47, s25, s47
	s_or_b32 s45, s45, s10
	s_cmp_eq_u32 s45, 0
	s_cbranch_scc1 .Lpf2_pedge
	global_load_dwordx2 v[20:21], v2, s[46:47]
	s_add_u32 s46, s46, 0x2200
	s_addc_u32 s47, s47, 0
	global_load_dwordx2 v[18:19], v2, s[46:47]
	s_add_u32 s46, s46, 0x2200
	s_addc_u32 s47, s47, 0
	global_load_dwordx2 v[22:23], v2, s[46:47]
	s_add_u32 s46, s46, 0x2200
	s_addc_u32 s47, s47, 0
	s_branch .Lpf2_pmain
.Lpf2_pedge:
	v_mov_b32_e32 v20, 0
	v_mov_b32_e32 v21, 0
	v_mov_b32_e32 v18, 0
	v_mov_b32_e32 v19, 0
	v_mov_b32_e32 v22, 0
	v_mov_b32_e32 v23, 0
	s_mov_b64 s[44:45], exec
	s_mov_b32 exec_lo, 0
	global_load_dwordx2 v[20:21], v2, s[46:47]
	s_add_u32 s46, s46, 0x2200
	s_addc_u32 s47, s47, 0
	global_load_dwordx2 v[18:19], v2, s[46:47]
	s_add_u32 s46, s46, 0x2200
	s_addc_u32 s47, s47, 0
	global_load_dwordx2 v[22:23], v2, s[46:47]
	s_add_u32 s46, s46, 0x2200
	s_addc_u32 s47, s47, 0
	s_mov_b64 exec, s[44:45]
.Lpf2_pmain:
	global_load_dwordx2 v[24:25], v2, s[46:47]
	s_add_u32 s46, s46, 0x2200
	s_addc_u32 s47, s47, 0
	global_load_dwordx2 v[26:27], v2, s[46:47]
	s_add_u32 s46, s46, 0x2200
	s_addc_u32 s47, s47, 0
	global_load_dwordx2 v[28:29], v2, s[46:47]
	s_add_u32 s46, s46, 0x2200
	s_addc_u32 s47, s47, 0
	global_load_dwordx2 v[30:31], v2, s[46:47]
	s_add_u32 s46, s46, 0x2200
	s_addc_u32 s47, s47, 0
	global_load_dwordx2 v[32:33], v2, s[46:47]
	s_add_u32 s46, s46, 0x2200
	s_addc_u32 s47, s47, 0
	global_load_dwordx2 v[34:35], v2, s[46:47]
	s_add_u32 s46, s46, 0x2200
	s_addc_u32 s47, s47, 0
	global_load_dwordx2 v[36:37], v2, s[46:47]
	s_add_u32 s46, s46, 0x2200
	s_addc_u32 s47, s47, 0
	global_load_dwordx2 v[38:39], v2, s[46:47]
	s_add_i32 s46, s13, s11
	s_add_i32 s46, s46, -3
	s_mul_i32 s46, s46, 0x2200
	s_ashr_i32 s47, s46, 31
	s_add_u32 s46, s24, s46
	s_addc_u32 s47, s25, s47
	s_or_b32 s45, s13, s10
	s_cmp_eq_u32 s45, 0
	s_cbranch_scc1 .Lpf2_qedge
	global_load_dword v70, v4, s[46:47]
	s_add_u32 s46, s46, 0x2200
	s_addc_u32 s47, s47, 0
	global_load_dword v69, v4, s[46:47]
	s_add_u32 s46, s46, 0x2200
	s_addc_u32 s47, s47, 0
	global_load_dword v72, v4, s[46:47]
	s_add_u32 s46, s46, 0x2200
	s_addc_u32 s47, s47, 0
	s_branch .Lpf2_qmain
.Lpf2_qedge:
	v_mov_b32_e32 v70, 0
	v_mov_b32_e32 v69, 0
	v_mov_b32_e32 v72, 0
	s_add_u32 s46, s46, 0x6600
	s_addc_u32 s47, s47, 0
.Lpf2_qmain:
	global_load_dword v71, v4, s[46:47]
	s_add_u32 s46, s46, 0x2200
	s_addc_u32 s47, s47, 0
	global_load_dword v74, v4, s[46:47]
	s_add_u32 s46, s46, 0x2200
	s_addc_u32 s47, s47, 0
	global_load_dword v73, v4, s[46:47]
	s_add_u32 s46, s46, 0x2200
	s_addc_u32 s47, s47, 0
	global_load_dword v76, v4, s[46:47]
	s_add_u32 s46, s46, 0x2200
	s_addc_u32 s47, s47, 0
	global_load_dword v75, v4, s[46:47]
	s_add_u32 s46, s46, 0x2200
	s_addc_u32 s47, s47, 0
	global_load_dword v78, v4, s[46:47]
	s_add_u32 s46, s46, 0x2200
	s_addc_u32 s47, s47, 0
	global_load_dword v77, v4, s[46:47]
	s_add_u32 s46, s46, 0x2200
	s_addc_u32 s47, s47, 0
	global_load_dword v79, v4, s[46:47]
.Lpf2_done:
	v_and_b32_e32 v0, 0x7f, v80
	v_ashrrev_i32_e32 v47, 3, v80
	v_and_b32_e32 v2, -16, v47
	v_lshlrev_b32_e32 v59, 1, v0
	s_movk_i32 s15, 0x110
	v_add_u32_e32 v3, 0, v59
	v_mul_lo_u32 v60, v2, s15
	v_add_u32_e32 v4, v3, v60
	v_or_b32_e32 v5, 15, v47
	s_waitcnt lgkmcnt(0)
	s_barrier
	ds_read_u16 v48, v4
	ds_read_u16 v49, v4 offset:272
	ds_read_u16 v61, v4 offset:544
	ds_read_u16 v62, v4 offset:816
	ds_read_u16 v63, v4 offset:1088
	ds_read_u16 v64, v4 offset:1360
	ds_read_u16 v65, v4 offset:1632
	ds_read_u16 v66, v4 offset:1904
	v_mul_lo_u32 v67, v5, s15
	v_add_u32_e32 v5, v3, v67
	ds_read_u16 v85, v4 offset:2176
	ds_read_u16 v86, v4 offset:2448
	ds_read_u16 v87, v4 offset:2720
	ds_read_u16 v88, v4 offset:2992
	ds_read_u16 v89, v4 offset:3264
	ds_read_u16 v90, v4 offset:3536
	ds_read_u16 v91, v4 offset:3808
	ds_read_u16 v92, v5
	v_mul_u32_u24_e32 v58, 0x90, v0
	v_mul_u32_u24_e32 v0, 0x8e, v0
	v_lshlrev_b32_e32 v93, 1, v2
	s_waitcnt lgkmcnt(8)
	v_perm_b32 v7, v66, v65, s78
	v_perm_b32 v6, v64, v63, s78
	v_perm_b32 v5, v62, v61, s78
	v_perm_b32 v4, v49, v48, s78
	v_add3_u32 v0, v3, v0, v93
	s_waitcnt lgkmcnt(0)
	v_perm_b32 v17, v92, v91, s78
	v_perm_b32 v16, v90, v89, s78
	v_perm_b32 v15, v88, v87, s78
	v_perm_b32 v14, v86, v85, s78
	ds_write_b128 v0, v[4:7] offset:17408
	ds_write_b128 v0, v[14:17] offset:17424
	v_bfe_u32 v0, v80, 1, 6
	v_or_b32_e32 v0, 64, v0
	s_ashr_i32 s8, s36, 9
	v_mul_lo_u16_e32 v3, 0x87, v0
	s_ashr_i32 s9, s8, 31
	v_lshrrev_b16_e32 v3, 13, v3
	s_movk_i32 s13, 0xffc3
	s_and_b32 s10, s61, 0xfc0
	s_lshl_b64 s[8:9], s[8:9], 12
	v_mad_i32_i24 v4, v3, s13, v0
	s_or_b32 s8, s8, s10
	v_ashrrev_i32_e32 v5, 31, v4
	v_lshl_add_u64 v[4:5], s[8:9], 0, v[4:5]
	v_mov_b64_e32 v[8:9], s[24:25]
	v_mad_u64_u32 v[6:7], s[10:11], v4, s87, v[8:9]
	v_mad_i32_i24 v7, v5, s87, v7
	v_lshlrev_b32_e32 v0, 11, v3
	v_lshl_add_u64 v[4:5], v[6:7], 0, v[0:1]
	s_lshl_b32 s62, s12, 1
	v_lshlrev_b32_e32 v0, 7, v80
	v_lshl_add_u64 v[4:5], v[4:5], 0, s[62:63]
	v_and_b32_e32 v0, 0x80, v0
	v_lshl_add_u64 v[4:5], v[4:5], 0, v[0:1]
	v_lshl_add_u32 v0, v2, 2, 0
	v_ashrrev_i32_e32 v3, 31, v2
	v_add_u32_e32 v0, 0x1e900, v0
	v_lshl_add_u64 v[44:45], v[2:3], 1, v[4:5]
	ds_read_b128 v[4:7], v0
	v_lshlrev_b32_e32 v57, 16, v49
	v_lshlrev_b32_e32 v56, 16, v48
	ds_read_b128 v[14:17], v0 offset:16
	ds_read_b128 v[48:51], v0 offset:32
	ds_read_b128 v[52:55], v0 offset:48
	v_and_b32_e32 v46, 15, v80
	s_waitcnt lgkmcnt(3)
	v_pk_mul_f32 v[4:5], v[4:5], v[56:57]
	v_lshlrev_b32_e32 v57, 16, v62
	v_lshlrev_b32_e32 v56, 16, v61
	v_pk_mul_f32 v[6:7], v[6:7], v[56:57]
	v_lshlrev_b32_e32 v57, 16, v64
	v_lshlrev_b32_e32 v56, 16, v63
	s_waitcnt lgkmcnt(2)
	v_pk_mul_f32 v[14:15], v[14:15], v[56:57]
	v_lshlrev_b32_e32 v57, 16, v66
	v_lshlrev_b32_e32 v56, 16, v65
	v_pk_mul_f32 v[16:17], v[16:17], v[56:57]
	v_lshlrev_b32_e32 v57, 16, v86
	v_lshlrev_b32_e32 v56, 16, v85
	s_waitcnt lgkmcnt(1)
	v_pk_mul_f32 v[48:49], v[48:49], v[56:57]
	v_lshlrev_b32_e32 v57, 16, v88
	v_lshlrev_b32_e32 v56, 16, v87
	v_pk_mul_f32 v[50:51], v[50:51], v[56:57]
	v_lshlrev_b32_e32 v57, 16, v90
	v_lshlrev_b32_e32 v56, 16, v89
	s_waitcnt lgkmcnt(0)
	v_pk_mul_f32 v[52:53], v[52:53], v[56:57]
	v_lshlrev_b32_e32 v57, 16, v92
	v_lshlrev_b32_e32 v56, 16, v91
	v_pk_mul_f32 v[54:55], v[54:55], v[56:57]
	v_cvt_pk_bf16_f32 v4, v4, v5
	v_cvt_pk_bf16_f32 v5, v6, v7
	v_cvt_pk_bf16_f32 v6, v14, v15
	v_cvt_pk_bf16_f32 v7, v16, v17
	v_cvt_pk_bf16_f32 v14, v48, v49
	v_cvt_pk_bf16_f32 v15, v50, v51
	v_cvt_pk_bf16_f32 v16, v52, v53
	v_cvt_pk_bf16_f32 v17, v54, v55
	global_store_dwordx4 v[44:45], v[4:7], off
	global_store_dwordx4 v[44:45], v[14:17], off offset:16
	v_add_u32_e32 v0, s2, v59
	v_add_u32_e32 v3, v0, v60
	v_add_u32_e32 v0, v0, v67
	ds_read_u16 v4, v3 offset:2176
	ds_read_u16 v14, v3 offset:2448
	ds_read_u16 v5, v3 offset:2720
	ds_read_u16 v15, v3 offset:2992
	ds_read_u16 v6, v3 offset:3264
	ds_read_u16 v16, v3 offset:3536
	ds_read_u16 v7, v3 offset:3808
	ds_read_u16 v0, v0
	ds_read_u16 v44, v3
	ds_read_u16 v45, v3 offset:272
	ds_read_u16 v48, v3 offset:544
	ds_read_u16 v49, v3 offset:816
	ds_read_u16 v50, v3 offset:1088
	ds_read_u16 v51, v3 offset:1360
	ds_read_u16 v17, v3 offset:1632
	ds_read_u16 v3, v3 offset:1904
	s_waitcnt lgkmcnt(8)
	v_perm_b32 v7, v0, v7, s78
	v_perm_b32 v6, v16, v6, s78
	v_perm_b32 v5, v15, v5, s78
	v_perm_b32 v4, v14, v4, s78
	s_waitcnt lgkmcnt(0)
	v_perm_b32 v17, v3, v17, s78
	v_perm_b32 v16, v51, v50, s78
	v_perm_b32 v15, v49, v48, s78
	v_perm_b32 v14, v45, v44, s78
	v_add3_u32 v0, 0, v58, v93
	ds_write_b128 v0, v[14:17] offset:35840
	ds_write_b128 v0, v[4:7] offset:35856
	v_lshlrev_b32_e32 v0, 5, v80
	v_mul_lo_u32 v4, v47, s15
	v_and_b32_e32 v0, 0xe0, v0
	v_readlane_b32 s2, v244, 12
	v_lshl_add_u32 v3, v47, 2, 0
	v_add_u32_e32 v3, 0x1e800, v3
	v_add3_u32 v14, s2, v4, v0
	ds_read_b128 v[4:7], v14
	ds_read_b32 v44, v3
	ds_read_b128 v[14:17], v14 offset:16
	s_mov_b32 s10, 0x4325c53f
	v_mul_hi_i32 v3, v47, s10
	s_movk_i32 s14, 0xffc3
	s_waitcnt lgkmcnt(2)
	v_lshlrev_b32_e32 v48, 16, v4
	v_and_b32_e32 v49, 0xffff0000, v4
	s_waitcnt lgkmcnt(1)
	v_pk_mul_f32 v[48:49], v[44:45], v[48:49] op_sel_hi:[0,1]
	v_cvt_pk_bf16_f32 v4, v48, v49
	v_lshlrev_b32_e32 v48, 16, v5
	v_and_b32_e32 v49, 0xffff0000, v5
	v_pk_mul_f32 v[48:49], v[44:45], v[48:49] op_sel_hi:[0,1]
	v_cvt_pk_bf16_f32 v5, v48, v49
	v_lshlrev_b32_e32 v48, 16, v6
	v_and_b32_e32 v49, 0xffff0000, v6
	v_pk_mul_f32 v[48:49], v[44:45], v[48:49] op_sel_hi:[0,1]
	v_cvt_pk_bf16_f32 v6, v48, v49
	v_lshlrev_b32_e32 v48, 16, v7
	v_and_b32_e32 v49, 0xffff0000, v7
	v_pk_mul_f32 v[48:49], v[44:45], v[48:49] op_sel_hi:[0,1]
	v_cvt_pk_bf16_f32 v7, v48, v49
	s_waitcnt lgkmcnt(0)
	v_lshlrev_b32_e32 v48, 16, v14
	v_and_b32_e32 v49, 0xffff0000, v14
	v_pk_mul_f32 v[48:49], v[44:45], v[48:49] op_sel_hi:[0,1]
	v_cvt_pk_bf16_f32 v14, v48, v49
	v_lshlrev_b32_e32 v48, 16, v15
	v_and_b32_e32 v49, 0xffff0000, v15
	v_pk_mul_f32 v[48:49], v[44:45], v[48:49] op_sel_hi:[0,1]
	v_cvt_pk_bf16_f32 v15, v48, v49
	v_lshlrev_b32_e32 v48, 16, v16
	v_and_b32_e32 v49, 0xffff0000, v16
	v_pk_mul_f32 v[48:49], v[44:45], v[48:49] op_sel_hi:[0,1]
	v_cvt_pk_bf16_f32 v16, v48, v49
	v_lshlrev_b32_e32 v48, 16, v17
	v_and_b32_e32 v49, 0xffff0000, v17
	v_pk_mul_f32 v[44:45], v[44:45], v[48:49] op_sel_hi:[0,1]
	v_cvt_pk_bf16_f32 v17, v44, v45
	v_lshrrev_b32_e32 v44, 31, v3
	v_ashrrev_i32_e32 v3, 4, v3
	v_add_u32_e32 v3, v3, v44
	v_mad_i32_i24 v44, v3, s13, v47
	v_ashrrev_i32_e32 v45, 31, v44
	v_lshl_add_u64 v[44:45], s[8:9], 0, v[44:45]
	v_mad_u64_u32 v[8:9], s[10:11], v44, s87, v[8:9]
	v_lshlrev_b32_e32 v44, 10, v3
	v_mad_i32_i24 v9, v45, s87, v9
	v_ashrrev_i32_e32 v45, 31, v44
	v_lshl_add_u64 v[8:9], v[44:45], 1, v[8:9]
	v_lshl_add_u64 v[8:9], v[8:9], 0, s[62:63]
	v_lshl_add_u64 v[8:9], v[8:9], 0, v[0:1]
	global_store_dwordx4 v[8:9], v[4:7], off
	global_store_dwordx4 v[8:9], v[14:17], off offset:16
	s_nop 0
	v_lshrrev_b32_e32 v4, 1, v80
	v_and_b32_e32 v4, 24, v4
	v_lshlrev_b32_e32 v3, 5, v43
	v_lshlrev_b32_e32 v48, 1, v4
	v_bfi_b32 v4, -16, v47, v80
	v_add_u32_e32 v61, 0, v48
	v_mul_lo_u32 v4, v4, s15
	v_and_or_b32 v62, v3, 32, v46
	v_add3_u32 v51, s2, v4, v48
	v_and_b32_e32 v47, 12, v84
	v_mad_u32_u24 v44, v62, s15, v61
	v_add_u32_e32 v50, v61, v4
	v_or_b32_e32 v49, v47, v2
	ds_read_b128 v[176:179], v44
	ds_read_b128 v[100:103], v50
	ds_read_b128 v[116:119], v51
	ds_read_b128 v[180:183], v44 offset:64
	ds_read_b128 v[104:107], v50 offset:64
	ds_read_b128 v[120:123], v51 offset:64
	ds_read_b128 v[184:187], v44 offset:128
	ds_read_b128 v[108:111], v50 offset:128
	ds_read_b128 v[124:127], v51 offset:128
	ds_read_b128 v[188:191], v44 offset:192
	ds_read_b128 v[112:115], v50 offset:192
	ds_read_b128 v[128:131], v51 offset:192
	v_or_b32_e32 v85, 16, v62
	s_movk_i32 s2, 0x110
	v_lshlrev_b32_e32 v52, 2, v49
	v_mad_u32_u24 v61, v85, s2, v61
	v_add_u32_e32 v54, 0x15c00, v52
	v_add_u32_e32 v55, 0x1ea00, v52
	v_lshlrev_b32_e32 v56, 2, v62
	v_add_u32_e32 v56, 0x15d00, v56
	ds_read_b128 v[206:209], v61
	ds_read_b128 v[210:213], v61 offset:64
	s_waitcnt lgkmcnt(13)
	s_waitcnt lgkmcnt(12)
	ds_read_b128 v[214:217], v61 offset:128
	ds_read_b128 v[218:221], v61 offset:192
	v_mfma_f32_16x16x32_bf16 v[6:9], v[100:103], v[176:179], 0
	v_lshrrev_b32_e32 v53, 1, v62
	v_and_b32_e32 v53, 28, v53
	v_add_u32_e32 v53, v53, v0
	s_waitcnt lgkmcnt(13)
	ds_read_b128 v[132:135], v54 offset:256
	v_mfma_f32_16x16x32_bf16 v[2:5], v[116:119], v[176:179], 0
	v_lshl_add_u32 v53, v49, 8, v53
	v_lshlrev_b32_e32 v92, 1, v62
	v_mov_b32_e32 v93, 0
	s_waitcnt lgkmcnt(13)
	s_waitcnt lgkmcnt(12)
	ds_read_b32 v222, v56
	ds_read_b32 v224, v56 offset:64
	v_mfma_f32_16x16x32_bf16 v[6:9], v[104:107], v[180:183], v[6:9]
	s_mov_b32 s2, 0x4325c53f
	v_or_b32_e32 v57, 1, v49
	v_or_b32_e32 v59, 2, v49
	s_waitcnt lgkmcnt(13)
	ds_read_b128 v[146:149], v54
	v_mfma_f32_16x16x32_bf16 v[2:5], v[120:123], v[180:183], v[2:5]
	v_or_b32_e32 v67, 3, v49
	v_ashrrev_i32_e32 v88, 1, v49
	v_add_u32_e32 v88, 0x80, v88
	s_waitcnt lgkmcnt(7)
	ds_read_b128 v[150:153], v54 offset:768
	ds_read_b32 v223, v56 offset:512
	ds_read_b32 v225, v56 offset:576
	ds_read_b128 v[154:157], v55
	v_mfma_f32_16x16x32_bf16 v[192:195], v[100:103], v[206:209], 0
	v_mul_hi_i32 v89, v88, s2
	v_lshrrev_b32_e32 v90, 31, v89
	v_ashrrev_i32_e32 v89, 4, v89
	v_mfma_f32_16x16x32_bf16 v[196:199], v[116:119], v[206:209], 0
	v_add_u32_e32 v89, v89, v90
	v_mad_i32_i24 v14, v89, s14, v88
	v_ashrrev_i32_e32 v15, 31, v14
	v_mfma_f32_16x16x32_bf16 v[6:9], v[108:111], v[184:187], v[6:9]
	v_lshl_add_u64 v[14:15], s[8:9], 0, v[14:15]
	v_mov_b64_e32 v[86:87], s[24:25]
	v_mad_u64_u32 v[86:87], s[10:11], v14, s87, v[86:87]
	v_mfma_f32_16x16x32_bf16 v[2:5], v[124:127], v[184:187], v[2:5]
	v_mov_b32_e32 v94, v87
	v_mov_b32_e32 v95, 0
	v_mad_u64_u32 v[14:15], s[10:11], v15, s87, v[94:95]
	s_waitcnt lgkmcnt(10)
	v_mfma_f32_16x16x32_bf16 v[192:195], v[104:107], v[210:213], v[192:195]
	v_mov_b32_e32 v87, v14
	v_lshlrev_b32_e32 v14, 10, v89
	v_ashrrev_i32_e32 v15, 31, v14
	v_mfma_f32_16x16x32_bf16 v[196:199], v[120:123], v[210:213], v[196:199]
	v_lshl_add_u64 v[14:15], v[14:15], 1, v[86:87]
	v_lshl_add_u64 v[14:15], v[14:15], 0, s[62:63]
	v_lshl_add_u64 v[14:15], v[14:15], 0, v[92:93]
	v_mfma_f32_16x16x32_bf16 v[6:9], v[112:115], v[188:191], v[6:9]
	v_ashrrev_i32_e32 v88, 1, v59
	v_add_u32_e32 v88, 0x80, v88
	v_mul_hi_i32 v89, v88, s2
	v_mfma_f32_16x16x32_bf16 v[2:5], v[128:131], v[188:191], v[2:5]
	v_lshrrev_b32_e32 v90, 31, v89
	v_ashrrev_i32_e32 v89, 4, v89
	v_add_u32_e32 v89, v89, v90
	s_waitcnt lgkmcnt(9)
	v_mfma_f32_16x16x32_bf16 v[192:195], v[108:111], v[214:217], v[192:195]
	v_mad_i32_i24 v16, v89, s14, v88
	v_ashrrev_i32_e32 v17, 31, v16
	v_lshl_add_u64 v[16:17], s[8:9], 0, v[16:17]
	v_mfma_f32_16x16x32_bf16 v[196:199], v[124:127], v[214:217], v[196:199]
	v_mov_b64_e32 v[86:87], s[24:25]
	v_mad_u64_u32 v[86:87], s[10:11], v16, s87, v[86:87]
	v_mov_b32_e32 v94, v87
	s_waitcnt lgkmcnt(8)
	v_mfma_f32_16x16x32_bf16 v[192:195], v[112:115], v[218:221], v[192:195]
	v_mov_b32_e32 v95, 0
	v_mad_u64_u32 v[16:17], s[10:11], v17, s87, v[94:95]
	v_mov_b32_e32 v87, v16
	v_mfma_f32_16x16x32_bf16 v[196:199], v[128:131], v[218:221], v[196:199]
	v_lshlrev_b32_e32 v16, 10, v89
	v_ashrrev_i32_e32 v17, 31, v16
	v_lshl_add_u64 v[16:17], v[16:17], 1, v[86:87]
	v_lshl_add_u64 v[16:17], v[16:17], 0, s[62:63]
	v_lshl_add_u64 v[16:17], v[16:17], 0, v[92:93]
	s_waitcnt lgkmcnt(5)
	v_sub_f32_e32 v226, v132, v222
	v_sub_f32_e32 v227, v133, v222
	v_sub_f32_e32 v228, v134, v222
	v_sub_f32_e32 v229, v135, v222
	v_sub_f32_e32 v230, v132, v224
	v_sub_f32_e32 v231, v133, v224
	v_sub_f32_e32 v232, v134, v224
	v_sub_f32_e32 v233, v135, v224
	v_mul_f32_e32 v226, 0x3fb8aa3b, v226
	v_mul_f32_e32 v227, 0x3fb8aa3b, v227
	v_mul_f32_e32 v228, 0x3fb8aa3b, v228
	v_mul_f32_e32 v229, 0x3fb8aa3b, v229
	v_mul_f32_e32 v230, 0x3fb8aa3b, v230
	v_mul_f32_e32 v231, 0x3fb8aa3b, v231
	v_mul_f32_e32 v232, 0x3fb8aa3b, v232
	v_mul_f32_e32 v233, 0x3fb8aa3b, v233
	v_exp_f32_e32 v226, v226
	v_exp_f32_e32 v227, v227
	v_exp_f32_e32 v228, v228
	v_exp_f32_e32 v229, v229
	v_exp_f32_e32 v230, v230
	v_exp_f32_e32 v231, v231
	v_exp_f32_e32 v232, v232
	v_exp_f32_e32 v233, v233
	s_waitcnt lgkmcnt(3)
	v_mul_f32_e32 v234, v146, v150
	v_mul_f32_e32 v235, v147, v151
	v_mul_f32_e32 v236, v148, v152
	v_mul_f32_e32 v237, v149, v153
	s_waitcnt lgkmcnt(0)
	v_mul_f32_e32 v44, v223, v234
	v_mul_f32_e32 v45, v223, v154
	v_mul_f32_e32 v44, v226, v44
	v_mul_f32_e32 v45, v226, v45
	v_mul_f32_e32 v44, v6, v44
	v_mul_f32_e32 v45, v2, v45
	v_cmp_lt_i32_e32 vcc, v62, v49
	v_cvt_pk_bf16_f32 v45, v45, v45
	v_cmp_le_i32_e64 s[10:11], v62, v49
	v_cndmask_b32_e32 v44, 0, v44, vcc
	s_nop 0
	v_cndmask_b32_e64 v45, 0, v45, s[10:11]
	ds_write_b32 v53, v44 offset:54272
	global_store_short v[14:15], v45, off
	v_mul_f32_e32 v44, v223, v235
	v_mul_f32_e32 v45, v223, v155
	v_mul_f32_e32 v44, v227, v44
	v_mul_f32_e32 v45, v227, v45
	v_mul_f32_e32 v44, v7, v44
	v_mul_f32_e32 v45, v3, v45
	v_cmp_lt_i32_e32 vcc, v62, v57
	v_cvt_pk_bf16_f32 v45, v45, v45
	v_cmp_le_i32_e64 s[10:11], v62, v57
	v_cndmask_b32_e32 v44, 0, v44, vcc
	s_nop 0
	v_cndmask_b32_e64 v45, 0, v45, s[10:11]
	ds_write_b32 v53, v44 offset:54528
	global_store_short v[14:15], v45, off offset:128
	v_mul_f32_e32 v44, v223, v236
	v_mul_f32_e32 v45, v223, v156
	v_mul_f32_e32 v44, v228, v44
	v_mul_f32_e32 v45, v228, v45
	v_mul_f32_e32 v44, v8, v44
	v_mul_f32_e32 v45, v4, v45
	v_cmp_lt_i32_e32 vcc, v62, v59
	v_cvt_pk_bf16_f32 v45, v45, v45
	v_cmp_le_i32_e64 s[10:11], v62, v59
	v_cndmask_b32_e32 v44, 0, v44, vcc
	s_nop 0
	v_cndmask_b32_e64 v45, 0, v45, s[10:11]
	ds_write_b32 v53, v44 offset:54784
	global_store_short v[16:17], v45, off
	v_mul_f32_e32 v44, v223, v237
	v_mul_f32_e32 v45, v223, v157
	v_mul_f32_e32 v44, v229, v44
	v_mul_f32_e32 v45, v229, v45
	v_mul_f32_e32 v44, v9, v44
	v_mul_f32_e32 v45, v5, v45
	v_cmp_lt_i32_e32 vcc, v62, v67
	v_cvt_pk_bf16_f32 v45, v45, v45
	v_cmp_le_i32_e64 s[10:11], v62, v67
	v_cndmask_b32_e32 v44, 0, v44, vcc
	s_nop 0
	v_cndmask_b32_e64 v45, 0, v45, s[10:11]
	ds_write_b32 v53, v44 offset:55040
	global_store_short v[16:17], v45, off offset:128
	v_mul_f32_e32 v44, v225, v234
	v_mul_f32_e32 v45, v225, v154
	v_mul_f32_e32 v44, v230, v44
	v_mul_f32_e32 v45, v230, v45
	v_mul_f32_e32 v44, v192, v44
	v_mul_f32_e32 v45, v196, v45
	v_cmp_lt_i32_e32 vcc, v85, v49
	v_cvt_pk_bf16_f32 v45, v45, v45
	v_cmp_le_i32_e64 s[10:11], v85, v49
	v_cndmask_b32_e32 v44, 0, v44, vcc
	s_nop 0
	v_cndmask_b32_e64 v45, 0, v45, s[10:11]
	ds_write_b32 v53, v44 offset:54280
	global_store_short v[14:15], v45, off offset:32
	v_mul_f32_e32 v44, v225, v235
	v_mul_f32_e32 v45, v225, v155
	v_mul_f32_e32 v44, v231, v44
	v_mul_f32_e32 v45, v231, v45
	v_mul_f32_e32 v44, v193, v44
	v_mul_f32_e32 v45, v197, v45
	v_cmp_lt_i32_e32 vcc, v85, v57
	v_cvt_pk_bf16_f32 v45, v45, v45
	v_cmp_le_i32_e64 s[10:11], v85, v57
	v_cndmask_b32_e32 v44, 0, v44, vcc
	s_nop 0
	v_cndmask_b32_e64 v45, 0, v45, s[10:11]
	ds_write_b32 v53, v44 offset:54536
	global_store_short v[14:15], v45, off offset:160
	v_mul_f32_e32 v44, v225, v236
	v_mul_f32_e32 v45, v225, v156
	v_mul_f32_e32 v44, v232, v44
	v_mul_f32_e32 v45, v232, v45
	v_mul_f32_e32 v44, v194, v44
	v_mul_f32_e32 v45, v198, v45
	v_cmp_lt_i32_e32 vcc, v85, v59
	v_cvt_pk_bf16_f32 v45, v45, v45
	v_cmp_le_i32_e64 s[10:11], v85, v59
	v_cndmask_b32_e32 v44, 0, v44, vcc
	s_nop 0
	v_cndmask_b32_e64 v45, 0, v45, s[10:11]
	ds_write_b32 v53, v44 offset:54792
	global_store_short v[16:17], v45, off offset:32
	v_mul_f32_e32 v44, v225, v237
	v_mul_f32_e32 v45, v225, v157
	v_mul_f32_e32 v44, v233, v44
	v_mul_f32_e32 v45, v233, v45
	v_mul_f32_e32 v44, v195, v44
	v_mul_f32_e32 v45, v199, v45
	v_cmp_lt_i32_e32 vcc, v85, v67
	v_cvt_pk_bf16_f32 v45, v45, v45
	v_cmp_le_i32_e64 s[10:11], v85, v67
	v_cndmask_b32_e32 v44, 0, v44, vcc
	s_nop 0
	v_cndmask_b32_e64 v45, 0, v45, s[10:11]
	ds_write_b32 v53, v44 offset:55048
	global_store_short v[16:17], v45, off offset:160
	s_add_i32 s2, s36, s50
	s_cmpk_gt_i32 s2, 0xfff
	s_cselect_b64 s[38:39], -1, 0
	s_cmpk_lt_i32 s2, 0x1000
	s_mov_b64 s[8:9], -1
	s_waitcnt lgkmcnt(0)
	s_barrier
	s_cbranch_scc1 .LBB0_569
	s_add_i32 s10, s61, s51
	s_mov_b64 s[8:9], 0
.LBB0_569:
	s_andn2_b64 vcc, exec, s[8:9]
	s_cbranch_vccnz .LBB0_600
	s_bfe_u32 s12, s2, 0x30006
	s_ashr_i32 s8, s2, 9
	s_add_i32 s61, s51, s61
	s_lshl_b32 s15, s12, 7
	s_and_b32 s10, s61, 0xfc0
	s_ashr_i32 s9, s8, 31
	s_lshl_b64 s[8:9], s[8:9], 12
	s_or_b32 s8, s8, s10
	s_mul_i32 s14, s9, 0x2200
	s_and_saveexec_b64 s[10:11], s[6:7]
	s_cbranch_execz .LBB0_522
	v_or_b32_e32 v0, s8, v81
	v_mov_b64_e32 v[2:3], s[24:25]
	v_mad_u64_u32 v[2:3], s[6:7], v0, s87, v[2:3]
	v_add_u32_e32 v3, s14, v3
	s_lshl_b32 s62, s12, 1
	v_lshl_add_u64 v[2:3], v[2:3], 0, s[62:63]
	v_add_co_u32_e32 v2, vcc, 0x2000, v2
	s_nop 1
	v_addc_co_u32_e32 v3, vcc, 0, v3, vcc
	global_load_ushort v41, v[2:3], off
	s_nop 0
	global_load_ushort v40, v[2:3], off offset:16
	s_branch .LBB0_522
